# v104: v103 but the acquire invalidate is issued by wave 1 right after the head barrier, in parallel with thread 0's arrival atomic / polling
# baseline (speedup 1.0000x reference)
.LBB0_119:
	s_cmp_gt_i32 s41, 1
	s_cselect_b64 s[6:7], -1, 0
	s_and_b64 s[8:9], s[22:23], s[6:7]
	s_andn2_b64 vcc, exec, s[8:9]
	s_cbranch_vccnz .LBB0_173
	s_mov_b64 s[10:11], s[0:1]
	s_getreg_b32 s3, hwreg(HW_REG_XCC_ID, 0, 4)
	s_waitcnt vmcnt(0)
	s_barrier
	v_readfirstlane_b32 s14, v158
	s_cmp_lg_u32 s14, 64
	s_cbranch_scc1 .Lsi_skip0
	buffer_inv sc1
	s_waitcnt vmcnt(0)
.Lsi_skip0:
	s_and_saveexec_b64 s[8:9], s[4:5]
	s_cbranch_execz .LBB0_172
	s_add_i32 s12, 0, 0x26c00
	v_mov_b32_e32 v0, s12
	s_load_dwordx2 s[10:11], s[10:11], 0x68
	s_waitcnt vmcnt(0) expcnt(0) lgkmcnt(0)
	ds_read_b32 v2, v0
	s_add_i32 s12, 0, 0x26c04
	v_mov_b32_e32 v0, s12
	ds_read_b32 v0, v0
	s_and_b32 s3, s3, 15
	s_waitcnt lgkmcnt(1)
	v_cmp_ne_u32_e32 vcc, 0, v2
	s_cbranch_vccnz .LBB0_136
	s_load_dwordx2 s[16:17], s[0:1], 0x78
	s_load_dword s15, s[0:1], 0x80
	s_add_u32 s12, s10, 0x60200
	s_addc_u32 s13, s11, 0
	s_add_u32 s14, s10, 0x60400
	s_waitcnt lgkmcnt(0)
	s_mul_i32 s33, s17, s16
	s_mul_i32 s33, s33, s15
	s_addc_u32 s15, s11, 0
	s_add_u32 s16, s10, 0x60500
	s_addc_u32 s17, s11, 0
	s_add_u32 s18, s10, 0x60600
	s_addc_u32 s19, s11, 0
	s_add_u32 s20, s10, 0x60700
	s_addc_u32 s21, s11, 0
	s_add_u32 s22, s10, 0x60800
	s_addc_u32 s23, s11, 0
	s_add_u32 s24, s10, 0x60900
	s_addc_u32 s25, s11, 0
	s_add_u32 s26, s10, 0x60a00
	s_addc_u32 s27, s11, 0
	s_add_u32 s28, s10, 0x60b00
	s_addc_u32 s29, s11, 0
	s_add_u32 s30, s10, 0x60c00
	s_addc_u32 s31, s11, 0
	s_add_u32 s34, s10, 0x60d00
	s_addc_u32 s35, s11, 0
	s_add_u32 s36, s10, 0x60e00
	s_addc_u32 s37, s11, 0
	s_add_u32 s38, s10, 0x60f00
	s_addc_u32 s39, s11, 0
	s_add_u32 s42, s10, 0x61000
	s_addc_u32 s43, s11, 0
	s_add_u32 s44, s10, 0x61100
	s_addc_u32 s45, s11, 0
	s_add_u32 s46, s10, 0x61200
	s_addc_u32 s47, s11, 0
	s_add_u32 s48, s10, 0x61300
	s_addc_u32 s49, s11, 0
	s_mov_b32 s56, 1
	v_mov_b32_e32 v16, 0
	s_branch .LBB0_124

.LBB0_217:
	s_cmp_gt_i32 s41, 2
	s_cselect_b64 s[6:7], -1, 0
	s_and_b64 s[8:9], s[12:13], s[6:7]
	s_andn2_b64 vcc, exec, s[8:9]
	s_cbranch_vccnz .LBB0_271
	s_mov_b64 s[10:11], s[0:1]
	s_getreg_b32 s3, hwreg(HW_REG_XCC_ID, 0, 4)
	s_waitcnt vmcnt(0)
	s_waitcnt vmcnt(0)
	s_barrier
	v_readfirstlane_b32 s14, v158
	s_cmp_lg_u32 s14, 64
	s_cbranch_scc1 .Lsi_skip1
	buffer_inv sc1
	s_waitcnt vmcnt(0)

.LBB0_285:
	s_cmp_gt_i32 s41, 3
	s_cselect_b64 s[6:7], -1, 0
	s_and_b64 s[8:9], s[42:43], s[6:7]
	s_andn2_b64 vcc, exec, s[8:9]
	s_cbranch_vccnz .LBB0_339
	s_mov_b64 s[10:11], s[0:1]
	s_getreg_b32 s3, hwreg(HW_REG_XCC_ID, 0, 4)
	s_waitcnt vmcnt(0)
	s_waitcnt vmcnt(0)
	s_barrier
	v_readfirstlane_b32 s14, v158
	s_cmp_lg_u32 s14, 64
	s_cbranch_scc1 .Lsi_skip2
	buffer_inv sc1
	s_waitcnt vmcnt(0)

.LBB0_352:
	s_cmp_gt_i32 s41, 4
	s_cselect_b64 s[6:7], -1, 0
	s_and_b64 s[8:9], s[22:23], s[6:7]
	s_andn2_b64 vcc, exec, s[8:9]
	s_cbranch_vccnz .LBB0_406
	s_mov_b64 s[10:11], s[0:1]
	s_getreg_b32 s3, hwreg(HW_REG_XCC_ID, 0, 4)
	s_waitcnt vmcnt(0)
	s_waitcnt vmcnt(0) lgkmcnt(0)
	s_barrier
	v_readfirstlane_b32 s14, v158
	s_cmp_lg_u32 s14, 64
	s_cbranch_scc1 .Lsi_skip3
	buffer_inv sc1
	s_waitcnt vmcnt(0)

.LBB0_411:
	s_cmp_gt_i32 s41, 5
	s_cselect_b64 s[6:7], -1, 0
	s_and_b64 s[8:9], s[12:13], s[6:7]
	s_andn2_b64 vcc, exec, s[8:9]
	s_cbranch_vccnz .LBB0_465
	s_mov_b64 s[10:11], s[0:1]
	s_getreg_b32 s3, hwreg(HW_REG_XCC_ID, 0, 4)
	s_waitcnt vmcnt(0)
	s_waitcnt vmcnt(0) lgkmcnt(0)
	s_barrier
	v_readfirstlane_b32 s14, v158
	s_cmp_lg_u32 s14, 64
	s_cbranch_scc1 .Lsi_skip4
	buffer_inv sc1
	s_waitcnt vmcnt(0)
.Lsi_skip4:
	s_and_saveexec_b64 s[8:9], s[4:5]
	s_cbranch_execz .LBB0_464
	s_load_dwordx2 s[4:5], s[10:11], 0x68
	s_add_i32 s10, 0, 0x26c00
	v_mov_b32_e32 v0, s10
	s_waitcnt vmcnt(0) expcnt(0) lgkmcnt(0)
	ds_read_b32 v2, v0
	s_add_i32 s10, 0, 0x26c04
	v_mov_b32_e32 v0, s10
	ds_read_b32 v0, v0
	s_and_b32 s3, s3, 15
	s_waitcnt lgkmcnt(1)
	v_cmp_ne_u32_e32 vcc, 0, v2
	s_cbranch_vccnz .LBB0_428
	s_load_dwordx2 s[14:15], s[0:1], 0x78
	s_load_dword s13, s[0:1], 0x80
	s_add_u32 s10, s4, 0x60200
	s_addc_u32 s11, s5, 0
	s_add_u32 s12, s4, 0x60400
	s_waitcnt lgkmcnt(0)
	s_mul_i32 s33, s15, s14
	s_mul_i32 s33, s33, s13
	s_addc_u32 s13, s5, 0
	s_add_u32 s14, s4, 0x60500
	s_addc_u32 s15, s5, 0
	s_add_u32 s16, s4, 0x60600
	s_addc_u32 s17, s5, 0
	s_add_u32 s18, s4, 0x60700
	s_addc_u32 s19, s5, 0
	s_add_u32 s20, s4, 0x60800
	s_addc_u32 s21, s5, 0
	s_add_u32 s22, s4, 0x60900
	s_addc_u32 s23, s5, 0
	s_add_u32 s24, s4, 0x60a00
	s_addc_u32 s25, s5, 0
	s_add_u32 s26, s4, 0x60b00
	s_addc_u32 s27, s5, 0
	s_add_u32 s28, s4, 0x60c00
	s_addc_u32 s29, s5, 0
	s_add_u32 s30, s4, 0x60d00
	s_addc_u32 s31, s5, 0
	s_add_u32 s34, s4, 0x60e00
	s_addc_u32 s35, s5, 0
	s_add_u32 s36, s4, 0x60f00
	s_addc_u32 s37, s5, 0
	s_add_u32 s38, s4, 0x61000
	s_addc_u32 s39, s5, 0
	s_add_u32 s42, s4, 0x61100
	s_addc_u32 s43, s5, 0
	s_add_u32 s44, s4, 0x61200
	s_addc_u32 s45, s5, 0
	s_add_u32 s46, s4, 0x61300
	s_addc_u32 s47, s5, 0
	s_mov_b32 s41, 1
	v_mov_b32_e32 v16, 0
	s_branch .LBB0_416
